# one static s_setprio 1 for waves 0-3 during the P1 and P8 GEMM unit loops (no other setprio)
# speedup vs baseline: 1.0027x; 1.0027x over previous
.LBB0_322:
	s_lshl_b32 s15, s14, 5
	s_mov_b64 s[10:11], 0x80
	s_and_b32 s50, s15, 0x60
	s_add_i32 m0, s40, 0x18000
	v_lshl_add_u64 v[8:9], v[8:9], 0, s[10:11]
	s_lshl_b32 s45, s7, 6
	s_lshl_b32 s5, s7, 13
	s_lshl_b32 s20, s50, 7
	s_waitcnt vmcnt(2)
	s_barrier
	global_load_lds_dwordx4 v[8:9], off
	v_lshl_add_u64 v[6:7], v[6:7], 0, s[10:11]
	s_add_i32 m0, s40, 0x1a000
	s_add_i32 s51, s40, 0x8000
	s_add_i32 s52, s40, 0xa000
	global_load_lds_dwordx4 v[6:7], off
	v_lshl_add_u64 v[2:3], v[2:3], 0, s[10:11]
	s_mov_b32 m0, s51
	s_add_u32 s18, s30, 0x40080
	global_load_lds_dwordx4 v[2:3], off
	v_lshl_add_u64 v[2:3], v[4:5], 0, s[10:11]
	s_mov_b32 m0, s52
	s_addc_u32 s19, s31, 0
	global_load_lds_dwordx4 v[2:3], off
	s_add_i32 m0, s40, 0x1c000
	v_lshl_add_u64 v[2:3], s[18:19], 0, v[202:203]
	global_load_lds_dwordx4 v[2:3], off
	v_lshl_add_u64 v[2:3], s[18:19], 0, v[198:199]
	s_add_i32 m0, s40, 0x1e000
	v_lshlrev_b32_e32 v4, 2, v216
	global_load_lds_dwordx4 v[2:3], off
	v_and_b32_e32 v2, 48, v0
	v_lshl_or_b32 v3, v216, 6, v2
	v_or_b32_e32 v2, v217, v2
	v_and_b32_e32 v4, 32, v4
	v_bitop3_b32 v225, s20, v2, v218 bitop3:0xf6
	v_lshlrev_b32_e32 v2, 8, v0
	v_bitop3_b32 v3, v3, s5, v4 bitop3:0xde
	v_and_b32_e32 v2, 0x18000, v2
	v_lshlrev_b32_e32 v4, 11, v12
	v_and_or_b32 v227, v0, 31, s15
	s_lshl_b32 s14, s14, 7
	s_add_i32 s15, 0, 0x21000
	v_or3_b32 v2, v10, v2, v4
	s_add_i32 s14, s15, s14
	v_add_u32_e32 v206, v2, v11
	v_lshlrev_b32_e32 v2, 4, v13
	s_waitcnt vmcnt(6)
	s_cmpk_lt_u32 s6, 0x100
	v_and_b32_e32 v2, 0x38000, v2
	s_cselect_b64 s[18:19], -1, 0
	s_lshl_b32 s6, s7, 8
	v_or3_b32 v2, v10, v2, v4
	s_sext_i32_i16 s2, s4
	v_lshrrev_b32_e32 v224, 4, v252
	v_cmp_gt_u32_e64 s[4:5], 32, v252
	v_lshl_add_u32 v228, v252, 2, s14
	s_add_i32 s14, s15, s6
	s_ashr_i32 s15, s3, 31
	v_mov_b32_e32 v207, v203
	v_add_u32_e32 v208, v2, v11
	v_mov_b32_e32 v209, v203
	v_mov_b64_e32 v[210:211], 0x580
	v_mov_b64_e32 v[212:213], 0x57f
	s_add_i32 s53, 0, 0x10000
	s_add_i32 s54, 0, 0x14000
	v_add_u32_e32 v229, 0, v3
	v_mov_b32_e32 v230, 0x358637bd
	s_movk_i32 s55, 0x1600
	s_barrier
	s_and_b64 vcc, exec, s[18:19]
	s_cbranch_vccz .Lpr1_skip
	s_setprio 1

.LBB0_1758:
	s_lshl_b32 s15, s14, 5
	s_mov_b64 s[16:17], 0x80
	s_and_b32 s50, s15, 0x60
	s_add_i32 m0, s40, 0x18000
	v_lshl_add_u64 v[8:9], v[8:9], 0, s[16:17]
	s_lshl_b32 s45, s7, 6
	s_lshl_b32 s5, s7, 13
	s_lshl_b32 s20, s50, 7
	s_waitcnt vmcnt(2)
	s_barrier
	global_load_lds_dwordx4 v[8:9], off
	v_lshl_add_u64 v[6:7], v[6:7], 0, s[16:17]
	s_add_i32 m0, s40, 0x1a000
	s_add_i32 s51, s40, 0x8000
	s_add_i32 s52, s40, 0xa000
	global_load_lds_dwordx4 v[6:7], off
	v_lshl_add_u64 v[2:3], v[2:3], 0, s[16:17]
	s_mov_b32 m0, s51
	s_add_u32 s18, s30, 0x40080
	global_load_lds_dwordx4 v[2:3], off
	v_lshl_add_u64 v[2:3], v[4:5], 0, s[16:17]
	s_mov_b32 m0, s52
	s_addc_u32 s19, s31, 0
	global_load_lds_dwordx4 v[2:3], off
	s_add_i32 m0, s40, 0x1c000
	v_lshl_add_u64 v[2:3], s[18:19], 0, v[202:203]
	global_load_lds_dwordx4 v[2:3], off
	v_lshl_add_u64 v[2:3], s[18:19], 0, v[198:199]
	s_add_i32 m0, s40, 0x1e000
	s_sext_i32_i16 s2, s4
	global_load_lds_dwordx4 v[2:3], off
	v_and_b32_e32 v1, 15, v0
	v_and_b32_e32 v2, 48, v0
	v_lshlrev_b32_e32 v4, 2, v0
	v_lshlrev_b32_e32 v5, 6, v0
	s_movk_i32 s4, 0x3c0
	v_lshl_or_b32 v3, v1, 6, v2
	v_and_b32_e32 v4, 32, v4
	v_and_or_b32 v2, v5, s4, v2
	v_bitop3_b32 v217, s20, v2, v4 bitop3:0xf6
	v_lshlrev_b32_e32 v2, 8, v0
	v_bitop3_b32 v3, v3, s5, v4 bitop3:0xde
	v_and_b32_e32 v2, 0x18000, v2
	v_lshlrev_b32_e32 v4, 11, v13
	v_and_or_b32 v218, v0, 31, s15
	s_lshl_b32 s14, s14, 7
	s_add_i32 s15, 0, 0x21000
	v_or3_b32 v2, v11, v2, v4
	s_add_i32 s14, s15, s14
	v_add_u32_e32 v206, v2, v12
	v_lshlrev_b32_e32 v2, 4, v10
	s_waitcnt vmcnt(6)
	s_cmpk_lt_u32 s6, 0x100
	v_and_b32_e32 v2, 0x38000, v2
	s_cselect_b64 s[18:19], -1, 0
	s_lshl_b32 s6, s7, 8
	v_or3_b32 v2, v11, v2, v4
	v_lshrrev_b32_e32 v216, 4, v252
	v_cmp_gt_u32_e64 s[4:5], 32, v252
	v_lshl_add_u32 v219, v252, 2, s14
	s_add_i32 s14, s15, s6
	s_ashr_i32 s15, s3, 31
	v_mov_b32_e32 v207, v203
	v_add_u32_e32 v208, v2, v12
	v_mov_b32_e32 v209, v203
	v_mov_b64_e32 v[210:211], 0x580
	v_mov_b64_e32 v[212:213], 0x57f
	s_add_i32 s53, 0, 0x10000
	s_add_i32 s54, 0, 0x14000
	v_add_u32_e32 v220, 0, v3
	v_mov_b32_e32 v221, 0x358637bd
	s_movk_i32 s55, 0x1600
	s_barrier
	s_and_b64 vcc, exec, s[18:19]
	s_cbranch_vccz .Lpr8_skip
	s_setprio 1
